# P10 final-norm and P0 rmsnorm: gain vectors kept in per-wave LDS copy, ds_read instead of serialized global gain loads with vmcnt(0) per chunk
# speedup vs baseline: 1.0046x; 1.0046x over previous
; #define GAS __attribute__((address_space(1)))
; #define INP(i) in_ptr(F.ka, (i))
; __device__ __forceinline__ void rms_row_to_bf16(const float* xrow, const float* g, bf16* orow, int lane) {
;     const GAS f32x4* xr = (const GAS f32x4*)xrow + lane;
;     f32x4 v[16]; float s = 0.f;
; #pragma unroll
;     for (int j = 0; j < 16; ++j) { v[j] = __builtin_nontemporal_load(&xr[64 * j]); s += (v[j].x * v[j].x + v[j].y * v[j].y) + (v[j].z * v[j].z + v[j].w * v[j].w); }
;     const float r = 1.f / sqrtf(wave_sum(s) * (1.f / DM) + EPS);
; __device__ __forceinline__ void p0_prologue(Frame& F) {
;     ...
;     for (int m = gw; m < MT; m += NGW) {
;         const float* xr = m < MP ? INP(0) + (size_t)m * DM : INP(1) + (size_t)(m - MP) * DM;
;         rms_row_to_bf16(xr, INP(6), WSP(bf16, WS_H) + (size_t)m * DM, F.lane);
.LBB0_40:
	s_or_b64 exec, exec, s[4:5]
	s_cmpk_lt_i32 s24, 0x4400
	s_cselect_b64 s[4:5], -1, 0
	v_writelane_b32 v255, s4, 7
	s_cmpk_gt_i32 s24, 0x43ff
	v_lshlrev_b32_e32 v166, 3, v194
	v_writelane_b32 v255, s5, 8
	v_mbcnt_lo_u32_b32 v195, -1, 0
	s_cbranch_scc1 .LBB0_47
	v_mov_b32_e32 v167, 0
	v_lshl_add_u64 v[2:3], s[22:23], 0, v[166:167]
	s_mov_b64 s[4:5], 0x1cc00000
	v_mbcnt_hi_u32_b32 v70, -1, v195
	v_lshl_add_u64 v[66:67], v[2:3], 0, s[4:5]
	s_ashr_i32 s25, s24, 31
	s_ashr_i32 s95, s94, 31
	v_and_b32_e32 v2, 64, v70
	s_lshl_b64 s[6:7], s[24:25], 14
	s_lshl_b64 s[8:9], s[94:95], 14
	s_mov_b32 s11, 0
	v_lshlrev_b32_e32 v68, 4, v194
	v_mov_b32_e32 v69, v167
	s_movk_i32 s2, 0x1000
	s_movk_i32 s26, 0x2000
	s_movk_i32 s27, 0x3000
	v_add_u32_e32 v71, 64, v2
	v_xor_b32_e32 v72, 1, v70
	v_xor_b32_e32 v73, 2, v70
	v_xor_b32_e32 v74, 4, v70
	v_xor_b32_e32 v75, 8, v70
	v_xor_b32_e32 v76, 16, v70
	v_xor_b32_e32 v77, 32, v70
	v_mov_b32_e32 v78, 0x358637bd
	s_mov_b32 s28, 0xf800000
	v_mov_b32_e32 v79, 0x260
	s_mov_b64 s[12:13], s[24:25]
	s_load_dwordx2 s[98:99], s[0:1], 0x30
	s_and_b32 s100, s24, 7
	s_lshl_b32 s100, s100, 14
	v_lshl_add_u32 v106, v194, 4, s100
	v_lshlrev_b32_e32 v107, 4, v194
	s_waitcnt lgkmcnt(0)
	global_load_dwordx4 v[108:111], v107, s[98:99]
	global_load_dwordx4 v[112:115], v107, s[98:99] offset:1024
	global_load_dwordx4 v[116:119], v107, s[98:99] offset:2048
	global_load_dwordx4 v[120:123], v107, s[98:99] offset:3072
	s_waitcnt vmcnt(0)
	ds_write_b128 v106, v[108:111]
	ds_write_b128 v106, v[112:115] offset:1024
	ds_write_b128 v106, v[116:119] offset:2048
	ds_write_b128 v106, v[120:123] offset:3072
	s_waitcnt lgkmcnt(0)
	v_add_u32_e32 v107, 0x1000, v107
	global_load_dwordx4 v[108:111], v107, s[98:99]
	global_load_dwordx4 v[112:115], v107, s[98:99] offset:1024
	global_load_dwordx4 v[116:119], v107, s[98:99] offset:2048
	global_load_dwordx4 v[120:123], v107, s[98:99] offset:3072
	s_waitcnt vmcnt(0)
	ds_write_b128 v106, v[108:111] offset:4096
	ds_write_b128 v106, v[112:115] offset:5120
	ds_write_b128 v106, v[116:119] offset:6144
	ds_write_b128 v106, v[120:123] offset:7168
	s_waitcnt lgkmcnt(0)
	v_add_u32_e32 v107, 0x1000, v107
	global_load_dwordx4 v[108:111], v107, s[98:99]
	global_load_dwordx4 v[112:115], v107, s[98:99] offset:1024
	global_load_dwordx4 v[116:119], v107, s[98:99] offset:2048
	global_load_dwordx4 v[120:123], v107, s[98:99] offset:3072
	s_waitcnt vmcnt(0)
	ds_write_b128 v106, v[108:111] offset:8192
	ds_write_b128 v106, v[112:115] offset:9216
	ds_write_b128 v106, v[116:119] offset:10240
	ds_write_b128 v106, v[120:123] offset:11264
	s_waitcnt lgkmcnt(0)
	v_add_u32_e32 v107, 0x1000, v107
	global_load_dwordx4 v[108:111], v107, s[98:99]
	global_load_dwordx4 v[112:115], v107, s[98:99] offset:1024
	global_load_dwordx4 v[116:119], v107, s[98:99] offset:2048
	global_load_dwordx4 v[120:123], v107, s[98:99] offset:3072
	s_waitcnt vmcnt(0)
	ds_write_b128 v106, v[108:111] offset:12288
	ds_write_b128 v106, v[112:115] offset:13312
	ds_write_b128 v106, v[116:119] offset:14336
	ds_write_b128 v106, v[120:123] offset:15360
	s_waitcnt lgkmcnt(0)
	s_branch .LBB0_43
.LBB0_42:
	v_lshl_add_u64 v[2:3], s[16:17], 0, v[68:69]
	s_mov_b64 s[4:5], s[0:1]
	v_add_co_u32_e32 v4, vcc, s26, v2
	global_load_dwordx4 v[62:65], v68, s[16:17] nt
	global_load_dwordx4 v[58:61], v68, s[16:17] offset:1024 nt
	global_load_dwordx4 v[54:57], v68, s[16:17] offset:2048 nt
	global_load_dwordx4 v[50:53], v68, s[16:17] offset:3072 nt
	v_addc_co_u32_e32 v5, vcc, 0, v3, vcc
	global_load_dwordx4 v[46:49], v[4:5], off offset:-4096 nt
	v_add_co_u32_e32 v6, vcc, s2, v2
	s_waitcnt vmcnt(3)
	v_mul_f32_e32 v86, v59, v59
	v_addc_co_u32_e32 v7, vcc, 0, v3, vcc
	global_load_dwordx4 v[42:45], v[6:7], off offset:1024 nt
	global_load_dwordx4 v[38:41], v[6:7], off offset:2048 nt
	global_load_dwordx4 v[34:37], v[6:7], off offset:3072 nt
	global_load_dwordx4 v[30:33], v[4:5], off nt
	global_load_dwordx4 v[26:29], v[4:5], off offset:1024 nt
	global_load_dwordx4 v[22:25], v[4:5], off offset:2048 nt
	global_load_dwordx4 v[18:21], v[4:5], off offset:3072 nt
	v_add_co_u32_e32 v84, vcc, s27, v2
	s_load_dwordx2 s[16:17], s[4:5], 0x30
	s_nop 0
	v_addc_co_u32_e32 v85, vcc, 0, v3, vcc
	global_load_dwordx4 v[14:17], v[84:85], off nt
	global_load_dwordx4 v[10:13], v[84:85], off offset:1024 nt
	global_load_dwordx4 v[6:9], v[84:85], off offset:2048 nt
	global_load_dwordx4 v[2:5], v[84:85], off offset:3072 nt
	s_waitcnt lgkmcnt(0)
	ds_read_b128 v[80:83], v106
	v_mul_f32_e32 v84, v63, v63
	v_mul_f32_e32 v85, v65, v65
	v_mul_f32_e32 v87, v61, v61
	s_waitcnt vmcnt(13)
	v_mul_f32_e32 v88, v55, v55
	v_mul_f32_e32 v89, v57, v57
	v_fmac_f32_e32 v84, v62, v62
	v_fmac_f32_e32 v85, v64, v64
	v_fmac_f32_e32 v86, v58, v58
	v_fmac_f32_e32 v87, v60, v60
	s_waitcnt vmcnt(12)
	v_mul_f32_e32 v90, v51, v51
	v_mul_f32_e32 v91, v53, v53
	v_fmac_f32_e32 v88, v54, v54
	v_fmac_f32_e32 v89, v56, v56
	v_add_f32_e32 v84, v84, v85
	v_add_f32_e32 v85, v86, v87
	v_fmac_f32_e32 v90, v50, v50
	v_fmac_f32_e32 v91, v52, v52
	s_waitcnt vmcnt(11)
	v_mul_f32_e32 v92, v47, v47
	v_mul_f32_e32 v93, v49, v49
	v_add_f32_e32 v86, v88, v89
	v_add_f32_e32 v84, v84, v85
	v_add_f32_e32 v87, v90, v91
	v_fmac_f32_e32 v92, v46, v46
	v_fmac_f32_e32 v93, v48, v48
	v_add_f32_e32 v84, v84, v86
	v_add_f32_e32 v85, v92, v93
	v_add_f32_e32 v84, v84, v87
	v_add_f32_e32 v84, v84, v85
	v_cmp_lt_i32_e32 vcc, v72, v71
	s_waitcnt vmcnt(10)
	v_mul_f32_e32 v94, v43, v43
	v_mul_f32_e32 v95, v45, v45
	s_waitcnt vmcnt(9)
	v_mul_f32_e32 v96, v39, v39
	v_mul_f32_e32 v97, v41, v41
	v_fmac_f32_e32 v94, v42, v42
	v_fmac_f32_e32 v95, v44, v44
	s_waitcnt vmcnt(8)
; __device__ __forceinline__ unsigned cvt_pk_bf16(float lo, float hi) { unsigned r; asm volatile("v_cvt_pk_bf16_f32 %0, %1, %2" : "=v"(r) : "v"(lo), "v"(hi)); return r; }
; #define GAS __attribute__((address_space(1)))
; __device__ __forceinline__ void rms_row_to_bf16(const float* xrow, const float* g, bf16* orow, int lane) {
;     ...
;     for (int j = 0; j < 16; ++j) { v[j] = __builtin_nontemporal_load(&xr[64 * j]); s += (v[j].x * v[j].x + v[j].y * v[j].y) + (v[j].z * v[j].z + v[j].w * v[j].w); }
;     const float r = 1.f / sqrtf(wave_sum(s) * (1.f / DM) + EPS);
;     const GAS f32x4* gr = (const GAS f32x4*)g + lane;
;     GAS v2u* o8 = (GAS v2u*)orow + lane;
; #pragma unroll
;     for (int j = 0; j < 16; ++j) { const f32x4 gg = gr[64 * j]; v2u w; w.x = cvt_pk_bf16(v[j].x * r * gg.x, v[j].y * r * gg.y); w.y = cvt_pk_bf16(v[j].z * r * gg.z, v[j].w * r * gg.w); o8[64 * j] = w; }
	v_mul_f32_e32 v98, v35, v35
	v_mul_f32_e32 v99, v37, v37
	v_fmac_f32_e32 v96, v38, v38
	v_fmac_f32_e32 v97, v40, v40
	v_add_f32_e32 v88, v94, v95
	s_waitcnt vmcnt(7)
	v_mul_f32_e32 v100, v31, v31
	v_mul_f32_e32 v101, v33, v33
	v_fmac_f32_e32 v98, v34, v34
	v_fmac_f32_e32 v99, v36, v36
	v_add_f32_e32 v89, v96, v97
	v_add_f32_e32 v84, v84, v88
	s_waitcnt vmcnt(6)
	v_mul_f32_e32 v102, v27, v27
	v_mul_f32_e32 v103, v29, v29
	v_fmac_f32_e32 v100, v30, v30
	v_fmac_f32_e32 v101, v32, v32
	v_add_f32_e32 v90, v98, v99
	v_add_f32_e32 v84, v84, v89
	s_waitcnt vmcnt(5)
	v_mul_f32_e32 v104, v23, v23
	v_fmac_f32_e32 v102, v26, v26
	v_fmac_f32_e32 v103, v28, v28
	v_add_f32_e32 v91, v100, v101
	v_add_f32_e32 v84, v84, v90
	v_mul_f32_e32 v85, v25, v25
	v_add_f32_e32 v92, v102, v103
	v_add_f32_e32 v84, v84, v91
	v_fmac_f32_e32 v104, v22, v22
	v_fmac_f32_e32 v85, v24, v24
	v_add_f32_e32 v84, v84, v92
	v_add_f32_e32 v85, v104, v85
	v_add_f32_e32 v84, v84, v85
	s_waitcnt vmcnt(4)
	v_mul_f32_e32 v85, v19, v19
	v_mul_f32_e32 v86, v21, v21
	v_fmac_f32_e32 v85, v18, v18
	v_fmac_f32_e32 v86, v20, v20
	v_add_f32_e32 v85, v85, v86
	v_add_f32_e32 v84, v84, v85
	s_waitcnt vmcnt(3)
	v_mul_f32_e32 v85, v15, v15
	v_mul_f32_e32 v86, v17, v17
	v_fmac_f32_e32 v85, v14, v14
	v_fmac_f32_e32 v86, v16, v16
	v_add_f32_e32 v85, v85, v86
	v_add_f32_e32 v84, v84, v85
	s_waitcnt vmcnt(2)
	v_mul_f32_e32 v85, v11, v11
	v_mul_f32_e32 v86, v13, v13
	v_fmac_f32_e32 v85, v10, v10
	v_fmac_f32_e32 v86, v12, v12
	v_add_f32_e32 v85, v85, v86
	v_add_f32_e32 v84, v84, v85
	s_waitcnt vmcnt(1)
	v_mul_f32_e32 v85, v7, v7
	v_mul_f32_e32 v86, v9, v9
	v_fmac_f32_e32 v85, v6, v6
	v_fmac_f32_e32 v86, v8, v8
	v_add_f32_e32 v85, v85, v86
	v_add_f32_e32 v84, v84, v85
	s_waitcnt vmcnt(0)
	v_mul_f32_e32 v85, v3, v3
	v_mul_f32_e32 v86, v5, v5
	v_fmac_f32_e32 v85, v2, v2
	v_fmac_f32_e32 v86, v4, v4
	v_add_f32_e32 v85, v85, v86
	v_add_f32_e32 v84, v84, v85
	v_cndmask_b32_e32 v85, v70, v72, vcc
	v_lshlrev_b32_e32 v85, 2, v85
	ds_bpermute_b32 v85, v85, v84
	v_cmp_lt_i32_e32 vcc, v73, v71
	s_waitcnt lgkmcnt(0)
	v_add_f32_e32 v84, v84, v85
	v_cndmask_b32_e32 v85, v70, v73, vcc
	v_lshlrev_b32_e32 v85, 2, v85
	ds_bpermute_b32 v85, v85, v84
	v_cmp_lt_i32_e32 vcc, v74, v71
	s_waitcnt lgkmcnt(0)
	v_add_f32_e32 v84, v84, v85
	v_cndmask_b32_e32 v85, v70, v74, vcc
	v_lshlrev_b32_e32 v85, 2, v85
	ds_bpermute_b32 v85, v85, v84
	v_cmp_lt_i32_e32 vcc, v75, v71
	s_waitcnt lgkmcnt(0)
	v_add_f32_e32 v84, v84, v85
	v_cndmask_b32_e32 v85, v70, v75, vcc
	v_lshlrev_b32_e32 v85, 2, v85
	ds_bpermute_b32 v85, v85, v84
	v_cmp_lt_i32_e32 vcc, v76, v71
	s_waitcnt lgkmcnt(0)
	v_add_f32_e32 v84, v84, v85
	v_cndmask_b32_e32 v85, v70, v76, vcc
	v_lshlrev_b32_e32 v85, 2, v85
	ds_bpermute_b32 v85, v85, v84
	v_cmp_lt_i32_e32 vcc, v77, v71
	s_waitcnt lgkmcnt(0)
	v_add_f32_e32 v84, v84, v85
	v_cndmask_b32_e32 v85, v70, v77, vcc
	v_lshlrev_b32_e32 v85, 2, v85
	ds_bpermute_b32 v85, v85, v84
	s_waitcnt lgkmcnt(0)
	v_add_f32_e32 v84, v84, v85
	v_fmamk_f32 v84, v84, 0x39800000, v78
	v_mul_f32_e32 v85, 0x4f800000, v84
	v_cmp_gt_f32_e32 vcc, s28, v84
	s_nop 1
	v_cndmask_b32_e32 v84, v84, v85, vcc
	v_sqrt_f32_e32 v85, v84
	s_nop 0
	v_add_u32_e32 v86, -1, v85
	v_fma_f32 v87, -v86, v85, v84
	v_cmp_ge_f32_e64 s[4:5], 0, v87
	v_add_u32_e32 v87, 1, v85
	s_nop 0
	v_cndmask_b32_e64 v86, v85, v86, s[4:5]
	v_fma_f32 v85, -v87, v85, v84
	v_cmp_lt_f32_e64 s[4:5], 0, v85
	s_nop 1
	v_cndmask_b32_e64 v85, v86, v87, s[4:5]
	v_mul_f32_e32 v86, 0x37800000, v85
	v_cndmask_b32_e32 v85, v85, v86, vcc
	v_cmp_class_f32_e32 vcc, v84, v79
	s_nop 1
	v_cndmask_b32_e32 v84, v85, v84, vcc
	v_div_scale_f32 v85, s[4:5], v84, v84, 1.0
	v_rcp_f32_e32 v86, v85
	s_lshl_b64 s[4:5], s[14:15], 13
	s_add_u32 s12, s12, s94
	s_addc_u32 s13, s13, s95
	v_fma_f32 v87, -v85, v86, 1.0
	v_fmac_f32_e32 v86, v87, v86
	v_div_scale_f32 v87, vcc, 1.0, v84, 1.0
	v_mul_f32_e32 v88, v87, v86
	v_fma_f32 v89, -v85, v88, v87
	v_fmac_f32_e32 v88, v89, v86
	v_fma_f32 v85, -v85, v88, v87
	v_div_fmas_f32 v85, v85, v86, v88
	v_div_fixup_f32 v86, v85, v84, 1.0
	v_mul_f32_e32 v62, v62, v86
	v_mul_f32_e32 v63, v63, v86
	s_waitcnt lgkmcnt(0)
	v_mul_f32_e32 v62, v80, v62
	v_mul_f32_e32 v63, v81, v63
	v_cvt_pk_bf16_f32 v62, v62, v63
	v_mul_f32_e32 v63, v64, v86
	v_lshl_add_u64 v[84:85], v[66:67], 0, s[4:5]
	v_mul_f32_e32 v63, v82, v63
	v_mul_f32_e32 v64, v65, v86
	v_mul_f32_e32 v64, v83, v64
	v_cvt_pk_bf16_f32 v63, v63, v64
	global_store_dwordx2 v[84:85], v[62:63], off
	s_nop 0
	ds_read_b128 v[62:65], v106 offset:1024
	v_mul_f32_e32 v58, v58, v86
	v_mul_f32_e32 v59, v59, v86
	v_mul_f32_e32 v60, v60, v86
	v_mul_f32_e32 v61, v61, v86
	v_mul_f32_e32 v54, v54, v86
	v_mul_f32_e32 v55, v55, v86
	v_mul_f32_e32 v56, v56, v86
	v_mul_f32_e32 v57, v57, v86
	v_mul_f32_e32 v50, v50, v86
	v_mul_f32_e32 v51, v51, v86
	v_mul_f32_e32 v52, v52, v86
	v_mul_f32_e32 v53, v53, v86
	v_mul_f32_e32 v46, v46, v86
	v_mul_f32_e32 v47, v47, v86
	v_mul_f32_e32 v48, v48, v86
	v_mul_f32_e32 v49, v49, v86
	v_mul_f32_e32 v42, v42, v86
	v_mul_f32_e32 v43, v43, v86
	v_mul_f32_e32 v44, v44, v86
	v_mul_f32_e32 v45, v45, v86
	v_mul_f32_e32 v38, v38, v86
	v_mul_f32_e32 v39, v39, v86
	v_mul_f32_e32 v40, v40, v86
	v_mul_f32_e32 v41, v41, v86
	v_mul_f32_e32 v34, v34, v86
	v_mul_f32_e32 v35, v35, v86
	v_mul_f32_e32 v36, v36, v86
	v_mul_f32_e32 v37, v37, v86
	v_mul_f32_e32 v30, v30, v86
	v_mul_f32_e32 v31, v31, v86
	v_mul_f32_e32 v32, v32, v86
	v_mul_f32_e32 v33, v33, v86
	v_mul_f32_e32 v26, v26, v86
	v_mul_f32_e32 v27, v27, v86
	v_mul_f32_e32 v28, v28, v86
	v_mul_f32_e32 v29, v29, v86
	v_mul_f32_e32 v22, v22, v86
	v_mul_f32_e32 v23, v23, v86
	v_mul_f32_e32 v24, v24, v86
	v_mul_f32_e32 v25, v25, v86
	v_mul_f32_e32 v18, v18, v86
	v_mul_f32_e32 v19, v19, v86
	v_mul_f32_e32 v20, v20, v86
	v_mul_f32_e32 v21, v21, v86
	v_mul_f32_e32 v14, v14, v86
	v_mul_f32_e32 v15, v15, v86
	v_mul_f32_e32 v16, v16, v86
	v_mul_f32_e32 v17, v17, v86
	v_mul_f32_e32 v10, v10, v86
	v_mul_f32_e32 v11, v11, v86
	v_mul_f32_e32 v12, v12, v86
	v_mul_f32_e32 v13, v13, v86
	v_mul_f32_e32 v6, v6, v86
	v_mul_f32_e32 v7, v7, v86
	v_mul_f32_e32 v8, v8, v86
	v_mul_f32_e32 v9, v9, v86
	s_add_u32 s6, s6, s8
	s_addc_u32 s7, s7, s9
	v_mul_f32_e32 v2, v2, v86
	v_mul_f32_e32 v3, v3, v86
	v_mul_f32_e32 v4, v4, v86
	v_mul_f32_e32 v5, v5, v86
	s_cmpk_gt_i32 s12, 0x43ff
	s_waitcnt lgkmcnt(0)
; __device__ __forceinline__ unsigned cvt_pk_bf16(float lo, float hi) { unsigned r; asm volatile("v_cvt_pk_bf16_f32 %0, %1, %2" : "=v"(r) : "v"(lo), "v"(hi)); return r; }
; __device__ __forceinline__ void rms_row_to_bf16(const float* xrow, const float* g, bf16* orow, int lane) {
;     ...
; #pragma unroll
;     for (int j = 0; j < 16; ++j) { const f32x4 gg = gr[64 * j]; v2u w; w.x = cvt_pk_bf16(v[j].x * r * gg.x, v[j].y * r * gg.y); w.y = cvt_pk_bf16(v[j].z * r * gg.z, v[j].w * r * gg.w); o8[64 * j] = w; }
	v_mul_f32_e32 v58, v62, v58
	v_mul_f32_e32 v59, v63, v59
	v_mul_f32_e32 v60, v64, v60
	v_mul_f32_e32 v61, v65, v61
	v_cvt_pk_bf16_f32 v58, v58, v59
	v_cvt_pk_bf16_f32 v59, v60, v61
	global_store_dwordx2 v[84:85], v[58:59], off offset:512
	s_nop 0
	ds_read_b128 v[58:61], v106 offset:2048
	s_waitcnt lgkmcnt(0)
	v_mul_f32_e32 v54, v54, v58
	v_mul_f32_e32 v55, v55, v59
	v_mul_f32_e32 v56, v56, v60
	v_mul_f32_e32 v57, v57, v61
	v_cvt_pk_bf16_f32 v54, v54, v55
	v_cvt_pk_bf16_f32 v55, v56, v57
	global_store_dwordx2 v[84:85], v[54:55], off offset:1024
	s_nop 0
	ds_read_b128 v[54:57], v106 offset:3072
	v_lshl_add_u64 v[58:59], s[16:17], 0, v[68:69]
	v_add_co_u32_e32 v60, vcc, s26, v58
	s_waitcnt lgkmcnt(0)
	v_mul_f32_e32 v50, v50, v54
	v_mul_f32_e32 v51, v51, v55
	v_addc_co_u32_e32 v61, vcc, 0, v59, vcc
	v_mul_f32_e32 v52, v52, v56
	v_mul_f32_e32 v53, v53, v57
	v_cvt_pk_bf16_f32 v50, v50, v51
	v_cvt_pk_bf16_f32 v51, v52, v53
	global_store_dwordx2 v[84:85], v[50:51], off offset:1536
	s_nop 0
	ds_read_b128 v[50:53], v106 offset:4096
	v_add_co_u32_e32 v54, vcc, s2, v58
	s_waitcnt lgkmcnt(0)
	v_mul_f32_e32 v46, v46, v50
	v_mul_f32_e32 v47, v47, v51
	v_addc_co_u32_e32 v55, vcc, 0, v59, vcc
	v_mul_f32_e32 v48, v48, v52
	v_mul_f32_e32 v49, v49, v53
	v_cvt_pk_bf16_f32 v46, v46, v47
	v_cvt_pk_bf16_f32 v47, v48, v49
	global_store_dwordx2 v[84:85], v[46:47], off offset:2048
	s_nop 0
	ds_read_b128 v[46:49], v106 offset:5120
	s_waitcnt lgkmcnt(0)
	v_mul_f32_e32 v42, v42, v46
	v_mul_f32_e32 v43, v43, v47
	v_mul_f32_e32 v44, v44, v48
	v_mul_f32_e32 v45, v45, v49
	v_cvt_pk_bf16_f32 v42, v42, v43
	v_cvt_pk_bf16_f32 v43, v44, v45
	global_store_dwordx2 v[84:85], v[42:43], off offset:2560
	s_nop 0
	ds_read_b128 v[42:45], v106 offset:6144
	s_waitcnt lgkmcnt(0)
	v_mul_f32_e32 v38, v38, v42
	v_mul_f32_e32 v39, v39, v43
	v_mul_f32_e32 v40, v40, v44
	v_mul_f32_e32 v41, v41, v45
	v_cvt_pk_bf16_f32 v38, v38, v39
	v_cvt_pk_bf16_f32 v39, v40, v41
	global_store_dwordx2 v[84:85], v[38:39], off offset:3072
	s_nop 0
	ds_read_b128 v[38:41], v106 offset:7168
	s_waitcnt lgkmcnt(0)
	v_mul_f32_e32 v34, v34, v38
	v_mul_f32_e32 v35, v35, v39
	v_mul_f32_e32 v36, v36, v40
	v_mul_f32_e32 v37, v37, v41
	v_cvt_pk_bf16_f32 v34, v34, v35
	v_cvt_pk_bf16_f32 v35, v36, v37
	global_store_dwordx2 v[84:85], v[34:35], off offset:3584
	s_nop 0
	ds_read_b128 v[34:37], v106 offset:8192
	v_add_co_u32_e32 v38, vcc, s2, v84
	s_waitcnt lgkmcnt(0)
	v_mul_f32_e32 v30, v30, v34
	v_addc_co_u32_e32 v39, vcc, 0, v85, vcc
	v_mul_f32_e32 v31, v31, v35
	v_mul_f32_e32 v32, v32, v36
	v_mul_f32_e32 v33, v33, v37
	v_cvt_pk_bf16_f32 v30, v30, v31
	v_cvt_pk_bf16_f32 v31, v32, v33
	global_store_dwordx2 v[38:39], v[30:31], off
	s_nop 0
	ds_read_b128 v[30:33], v106 offset:9216
	s_waitcnt lgkmcnt(0)
	v_mul_f32_e32 v26, v26, v30
	v_mul_f32_e32 v27, v27, v31
	v_mul_f32_e32 v28, v28, v32
	v_mul_f32_e32 v29, v29, v33
	v_cvt_pk_bf16_f32 v26, v26, v27
	v_cvt_pk_bf16_f32 v27, v28, v29
	global_store_dwordx2 v[38:39], v[26:27], off offset:512
	s_nop 0
	ds_read_b128 v[26:29], v106 offset:10240
	s_waitcnt lgkmcnt(0)
	v_mul_f32_e32 v22, v22, v26
	v_mul_f32_e32 v23, v23, v27
	v_mul_f32_e32 v24, v24, v28
	v_mul_f32_e32 v25, v25, v29
	v_cvt_pk_bf16_f32 v22, v22, v23
	v_cvt_pk_bf16_f32 v23, v24, v25
	global_store_dwordx2 v[38:39], v[22:23], off offset:1024
	s_nop 0
	ds_read_b128 v[22:25], v106 offset:11264
	v_add_co_u32_e32 v26, vcc, s27, v58
	s_waitcnt lgkmcnt(0)
	v_mul_f32_e32 v18, v18, v22
	v_mul_f32_e32 v19, v19, v23
	v_addc_co_u32_e32 v27, vcc, 0, v59, vcc
	v_mul_f32_e32 v20, v20, v24
	v_mul_f32_e32 v21, v21, v25
	v_cvt_pk_bf16_f32 v18, v18, v19
	v_cvt_pk_bf16_f32 v19, v20, v21
	global_store_dwordx2 v[38:39], v[18:19], off offset:1536
	s_nop 0
	ds_read_b128 v[18:21], v106 offset:12288
	s_waitcnt lgkmcnt(0)
	v_mul_f32_e32 v14, v14, v18
	v_mul_f32_e32 v15, v15, v19
	v_mul_f32_e32 v16, v16, v20
	v_mul_f32_e32 v17, v17, v21
	v_cvt_pk_bf16_f32 v14, v14, v15
	v_cvt_pk_bf16_f32 v15, v16, v17
	global_store_dwordx2 v[38:39], v[14:15], off offset:2048
	s_nop 0
	ds_read_b128 v[14:17], v106 offset:13312
	s_waitcnt lgkmcnt(0)
	v_mul_f32_e32 v10, v10, v14
	v_mul_f32_e32 v11, v11, v15
	v_mul_f32_e32 v12, v12, v16
	v_mul_f32_e32 v13, v13, v17
	v_cvt_pk_bf16_f32 v10, v10, v11
	v_cvt_pk_bf16_f32 v11, v12, v13
	global_store_dwordx2 v[38:39], v[10:11], off offset:2560
	s_nop 0
	ds_read_b128 v[10:13], v106 offset:14336
	s_waitcnt lgkmcnt(0)
	v_mul_f32_e32 v6, v6, v10
	v_mul_f32_e32 v7, v7, v11
	v_mul_f32_e32 v8, v8, v12
	v_mul_f32_e32 v9, v9, v13
	v_cvt_pk_bf16_f32 v6, v6, v7
	v_cvt_pk_bf16_f32 v7, v8, v9
	global_store_dwordx2 v[38:39], v[6:7], off offset:3072
	s_nop 0
	ds_read_b128 v[6:9], v106 offset:15360
	s_waitcnt lgkmcnt(0)
	v_mul_f32_e32 v2, v2, v6
	v_mul_f32_e32 v3, v3, v7
	v_mul_f32_e32 v4, v4, v8
	v_mul_f32_e32 v5, v5, v9
	v_cvt_pk_bf16_f32 v2, v2, v3
	v_cvt_pk_bf16_f32 v3, v4, v5
	global_store_dwordx2 v[38:39], v[2:3], off offset:3584
	s_cbranch_scc1 .LBB0_47

; __device__ __forceinline__ float bf_lo(unsigned w) { return __uint_as_float(w << 16); }
; __device__ __forceinline__ float bf_hi(unsigned w) { return __uint_as_float(w & 0xffff0000u); }
; __device__ __forceinline__ v4u pack8(f32x4 a, f32x4 b) { v4u w; w.x = cvt_pk_bf16(a[0], a[1]); w.y = cvt_pk_bf16(a[2], a[3]); w.z = cvt_pk_bf16(b[0], b[1]); w.w = cvt_pk_bf16(b[2], b[3]); return w; }
;     __device__ __forceinline__ void operator()(const f32x4 (&acc)[2][2][4][2], const Unit& u, int wr, int wc, int fr, int fq) const {
;         const bf16* const X1B = (const bf16*)(ws + WS_X1B); bf16* const X2B = (bf16*)(ws + WS_X2B);
;         const int col0 = u.pn * 256 + wc * 32 + 8 * fq;
; #pragma unroll
;         for (int ai = 0; ai < 2; ++ai)
; #pragma unroll
;             for (int m = 0; m < 4; ++m) { const int p = ai * 128 + wr * 64 + m * 16 + fr;
;                 const bf16* sr = X1B + (size_t)(u.pm * 256 + perm_row(p)) * DM + col0; bf16* dr = X2B + (size_t)(u.pm * 256 + p) * DM + col0;
; #pragma unroll
;                 for (int bj = 0; bj < 2; ++bj) { const v4u x = *(const v4u*)(sr + bj * 128); const f32x4 a0 = acc[ai][bj][m][0], a1 = acc[ai][bj][m][1];
;                     const f32x4 v0 = {bf_lo(x.x) + a0[0], bf_hi(x.x) + a0[1], bf_lo(x.y) + a0[2], bf_hi(x.y) + a0[3]};
;                     const f32x4 v1 = {bf_lo(x.z) + a1[0], bf_hi(x.z) + a1[1], bf_lo(x.w) + a1[2], bf_hi(x.w) + a1[3]};
;                     *(v4u*)(dr + bj * 128) = pack8(v0, v1); } }
;     }
.LBB0_1734:
	s_lshl_b32 s40, s46, 8
	v_or_b32_e32 v169, s40, v149
	v_lshl_or_b32 v146, s47, 8, v165
	v_add_u32_e32 v178, s30, v169
	v_ashrrev_i32_e32 v147, 31, v146
	v_or_b32_e32 v170, v178, v150
	v_lshlrev_b64 v[174:175], 1, v[146:147]
	v_ashrrev_i32_e32 v171, 31, v170
	v_lshl_add_u64 v[146:147], s[14:15], 0, v[174:175]
	v_lshlrev_b64 v[170:171], 13, v[170:171]
	v_lshl_add_u64 v[176:177], v[146:147], 0, v[170:171]
	global_load_dwordx4 v[170:173], v[176:177], off
	s_and_b64 vcc, exec, s[4:5]
	s_mov_b64 s[4:5], -1
	s_waitcnt vmcnt(0)
	v_lshlrev_b32_e32 v179, 16, v170
	v_and_b32_e32 v170, 0xffff0000, v170
	v_lshlrev_b32_e32 v180, 16, v171
	v_and_b32_e32 v171, 0xffff0000, v171
	v_lshlrev_b32_e32 v182, 16, v173
	v_and_b32_e32 v173, 0xffff0000, v173
	v_lshlrev_b32_e32 v181, 16, v172
	v_and_b32_e32 v172, 0xffff0000, v172
	v_add_f32_e32 v126, v126, v179
	v_add_f32_e32 v127, v127, v170
	v_add_f32_e32 v129, v129, v171
	v_add_f32_e32 v170, v124, v182
	v_add_f32_e32 v171, v125, v173
	v_add_f32_e32 v128, v128, v180
	v_add_f32_e32 v122, v122, v181
	v_add_f32_e32 v123, v123, v172
	v_cvt_pk_bf16_f32 v124, v126, v127
	v_cvt_pk_bf16_f32 v125, v128, v129
	v_cvt_pk_bf16_f32 v126, v122, v123
	v_cvt_pk_bf16_f32 v127, v170, v171
	global_load_dwordx4 v[170:173], v[176:177], off offset:256
	v_add_u32_e32 v128, s40, v1
	v_ashrrev_i32_e32 v129, 31, v128
	v_lshl_add_u64 v[122:123], s[36:37], 0, v[174:175]
	v_lshlrev_b64 v[128:129], 13, v[128:129]
	v_or_b32_e32 v174, v178, v152
	v_lshl_add_u64 v[128:129], v[122:123], 0, v[128:129]
	v_ashrrev_i32_e32 v175, 31, v174
	v_lshlrev_b64 v[174:175], 13, v[174:175]
	global_store_dwordx4 v[128:129], v[124:127], off
	v_lshl_add_u64 v[174:175], v[146:147], 0, v[174:175]
	s_waitcnt vmcnt(1)
	v_lshlrev_b32_e32 v124, 16, v170
	v_and_b32_e32 v125, 0xffff0000, v170
	v_lshlrev_b32_e32 v126, 16, v171
	v_and_b32_e32 v127, 0xffff0000, v171
	v_lshlrev_b32_e32 v170, 16, v172
	v_and_b32_e32 v171, 0xffff0000, v172
	v_lshlrev_b32_e32 v172, 16, v173
	v_and_b32_e32 v173, 0xffff0000, v173
	v_add_f32_e32 v118, v118, v124
	v_add_f32_e32 v119, v119, v125
	v_add_f32_e32 v120, v120, v126
	v_add_f32_e32 v121, v121, v127
	v_add_f32_e32 v117, v117, v173
	v_add_f32_e32 v124, v114, v170
	v_add_f32_e32 v125, v115, v171
	v_add_f32_e32 v126, v116, v172
	v_cvt_pk_bf16_f32 v114, v118, v119
	v_cvt_pk_bf16_f32 v115, v120, v121
	v_cvt_pk_bf16_f32 v116, v124, v125
	v_cvt_pk_bf16_f32 v117, v126, v117
	global_load_dwordx4 v[118:121], v[174:175], off
	s_nop 0
	global_store_dwordx4 v[128:129], v[114:117], off offset:256
	s_waitcnt vmcnt(1)
	s_nop 0
	v_lshlrev_b32_e32 v114, 16, v118
	v_and_b32_e32 v115, 0xffff0000, v118
	v_lshlrev_b32_e32 v116, 16, v119
	v_and_b32_e32 v117, 0xffff0000, v119
	v_lshlrev_b32_e32 v118, 16, v120
	v_and_b32_e32 v119, 0xffff0000, v120
	v_lshlrev_b32_e32 v120, 16, v121
	v_and_b32_e32 v121, 0xffff0000, v121
	v_add_f32_e32 v110, v110, v114
	v_add_f32_e32 v111, v111, v115
	v_add_f32_e32 v112, v112, v116
	v_add_f32_e32 v113, v113, v117
	v_add_f32_e32 v109, v109, v121
	v_add_f32_e32 v114, v106, v118
	v_add_f32_e32 v115, v107, v119
	v_add_f32_e32 v116, v108, v120
	v_cvt_pk_bf16_f32 v106, v110, v111
	v_cvt_pk_bf16_f32 v107, v112, v113
	v_cvt_pk_bf16_f32 v108, v114, v115
	v_cvt_pk_bf16_f32 v109, v116, v109
	global_load_dwordx4 v[110:113], v[174:175], off offset:256
	v_add_u32_e32 v114, s40, v151
	v_ashrrev_i32_e32 v115, 31, v114
	v_lshlrev_b64 v[114:115], 13, v[114:115]
	v_or_b32_e32 v116, v178, v154
	v_lshl_add_u64 v[114:115], v[122:123], 0, v[114:115]
	v_ashrrev_i32_e32 v117, 31, v116
	v_lshlrev_b64 v[116:117], 13, v[116:117]
	global_store_dwordx4 v[114:115], v[106:109], off
	v_lshl_add_u64 v[116:117], v[146:147], 0, v[116:117]
	s_waitcnt vmcnt(1)
	v_lshlrev_b32_e32 v106, 16, v110
	v_and_b32_e32 v107, 0xffff0000, v110
	v_lshlrev_b32_e32 v108, 16, v111
	v_and_b32_e32 v109, 0xffff0000, v111
	v_lshlrev_b32_e32 v110, 16, v112
	v_and_b32_e32 v111, 0xffff0000, v112
	v_lshlrev_b32_e32 v112, 16, v113
	v_and_b32_e32 v113, 0xffff0000, v113
	v_add_f32_e32 v102, v102, v106
	v_add_f32_e32 v103, v103, v107
	v_add_f32_e32 v104, v104, v108
	v_add_f32_e32 v105, v105, v109
	v_add_f32_e32 v101, v101, v113
	v_add_f32_e32 v106, v98, v110
	v_add_f32_e32 v107, v99, v111
	v_add_f32_e32 v108, v100, v112
	v_cvt_pk_bf16_f32 v98, v102, v103
	v_cvt_pk_bf16_f32 v99, v104, v105
	v_cvt_pk_bf16_f32 v100, v106, v107
	v_cvt_pk_bf16_f32 v101, v108, v101
	global_load_dwordx4 v[102:105], v[116:117], off
	s_nop 0
	global_store_dwordx4 v[114:115], v[98:101], off offset:256
	s_waitcnt vmcnt(1)
	s_nop 0
	v_lshlrev_b32_e32 v98, 16, v102
	v_and_b32_e32 v99, 0xffff0000, v102
	v_lshlrev_b32_e32 v100, 16, v103
	v_and_b32_e32 v101, 0xffff0000, v103
	v_lshlrev_b32_e32 v102, 16, v104
	v_and_b32_e32 v103, 0xffff0000, v104
	v_lshlrev_b32_e32 v104, 16, v105
	v_and_b32_e32 v105, 0xffff0000, v105
	v_add_f32_e32 v94, v94, v98
	v_add_f32_e32 v95, v95, v99
	v_add_f32_e32 v96, v96, v100
	v_add_f32_e32 v97, v97, v101
	v_add_f32_e32 v93, v93, v105
	v_add_f32_e32 v98, v90, v102
	v_add_f32_e32 v99, v91, v103
	v_add_f32_e32 v100, v92, v104
	v_cvt_pk_bf16_f32 v90, v94, v95
	v_cvt_pk_bf16_f32 v91, v96, v97
	v_cvt_pk_bf16_f32 v92, v98, v99
	v_cvt_pk_bf16_f32 v93, v100, v93
	global_load_dwordx4 v[94:97], v[116:117], off offset:256
	v_add_u32_e32 v98, s40, v153
	v_ashrrev_i32_e32 v99, 31, v98
	v_lshlrev_b64 v[98:99], 13, v[98:99]
	v_or_b32_e32 v100, v178, v156
	v_lshl_add_u64 v[98:99], v[122:123], 0, v[98:99]
	v_ashrrev_i32_e32 v101, 31, v100
	v_lshlrev_b64 v[100:101], 13, v[100:101]
	global_store_dwordx4 v[98:99], v[90:93], off
	v_lshl_add_u64 v[100:101], v[146:147], 0, v[100:101]
	s_waitcnt vmcnt(1)
; __device__ __forceinline__ float bf_lo(unsigned w) { return __uint_as_float(w << 16); }
; __device__ __forceinline__ float bf_hi(unsigned w) { return __uint_as_float(w & 0xffff0000u); }
; __device__ __forceinline__ v4u pack8(f32x4 a, f32x4 b) { v4u w; w.x = cvt_pk_bf16(a[0], a[1]); w.y = cvt_pk_bf16(a[2], a[3]); w.z = cvt_pk_bf16(b[0], b[1]); w.w = cvt_pk_bf16(b[2], b[3]); return w; }
;     __device__ __forceinline__ void operator()(const f32x4 (&acc)[2][2][4][2], const Unit& u, int wr, int wc, int fr, int fq) const {
;         const bf16* const X1B = (const bf16*)(ws + WS_X1B); bf16* const X2B = (bf16*)(ws + WS_X2B);
;         const int col0 = u.pn * 256 + wc * 32 + 8 * fq;
; #pragma unroll
;         for (int ai = 0; ai < 2; ++ai)
; #pragma unroll
;             for (int m = 0; m < 4; ++m) { const int p = ai * 128 + wr * 64 + m * 16 + fr;
;                 const bf16* sr = X1B + (size_t)(u.pm * 256 + perm_row(p)) * DM + col0; bf16* dr = X2B + (size_t)(u.pm * 256 + p) * DM + col0;
; #pragma unroll
;                 for (int bj = 0; bj < 2; ++bj) { const v4u x = *(const v4u*)(sr + bj * 128); const f32x4 a0 = acc[ai][bj][m][0], a1 = acc[ai][bj][m][1];
;                     const f32x4 v0 = {bf_lo(x.x) + a0[0], bf_hi(x.x) + a0[1], bf_lo(x.y) + a0[2], bf_hi(x.y) + a0[3]};
;                     const f32x4 v1 = {bf_lo(x.z) + a1[0], bf_hi(x.z) + a1[1], bf_lo(x.w) + a1[2], bf_hi(x.w) + a1[3]};
;                     *(v4u*)(dr + bj * 128) = pack8(v0, v1); } }
;     }
	v_lshlrev_b32_e32 v90, 16, v94
	v_and_b32_e32 v91, 0xffff0000, v94
	v_lshlrev_b32_e32 v92, 16, v95
	v_and_b32_e32 v93, 0xffff0000, v95
	v_lshlrev_b32_e32 v94, 16, v96
	v_and_b32_e32 v95, 0xffff0000, v96
	v_lshlrev_b32_e32 v96, 16, v97
	v_and_b32_e32 v97, 0xffff0000, v97
	v_add_f32_e32 v86, v86, v90
	v_add_f32_e32 v87, v87, v91
	v_add_f32_e32 v88, v88, v92
	v_add_f32_e32 v89, v89, v93
	v_add_f32_e32 v85, v85, v97
	v_add_f32_e32 v90, v82, v94
	v_add_f32_e32 v91, v83, v95
	v_add_f32_e32 v92, v84, v96
	v_cvt_pk_bf16_f32 v82, v86, v87
	v_cvt_pk_bf16_f32 v83, v88, v89
	v_cvt_pk_bf16_f32 v84, v90, v91
	v_cvt_pk_bf16_f32 v85, v92, v85
	global_load_dwordx4 v[86:89], v[100:101], off
	s_nop 0
	global_store_dwordx4 v[98:99], v[82:85], off offset:256
	s_waitcnt vmcnt(1)
	s_nop 0
	v_lshlrev_b32_e32 v82, 16, v86
	v_and_b32_e32 v83, 0xffff0000, v86
	v_lshlrev_b32_e32 v84, 16, v87
	v_and_b32_e32 v85, 0xffff0000, v87
	v_lshlrev_b32_e32 v86, 16, v88
	v_and_b32_e32 v87, 0xffff0000, v88
	v_lshlrev_b32_e32 v88, 16, v89
	v_and_b32_e32 v89, 0xffff0000, v89
	v_add_f32_e32 v78, v78, v82
	v_add_f32_e32 v79, v79, v83
	v_add_f32_e32 v80, v80, v84
	v_add_f32_e32 v81, v81, v85
	v_add_f32_e32 v77, v77, v89
	v_add_f32_e32 v82, v74, v86
	v_add_f32_e32 v83, v75, v87
	v_add_f32_e32 v84, v76, v88
	v_cvt_pk_bf16_f32 v74, v78, v79
	v_cvt_pk_bf16_f32 v75, v80, v81
	v_cvt_pk_bf16_f32 v76, v82, v83
	v_cvt_pk_bf16_f32 v77, v84, v77
	global_load_dwordx4 v[78:81], v[100:101], off offset:256
	v_add_u32_e32 v82, s40, v155
	v_ashrrev_i32_e32 v83, 31, v82
	v_add_u32_e32 v86, s33, v169
	v_lshlrev_b64 v[82:83], 13, v[82:83]
	v_or_b32_e32 v84, v86, v158
	v_lshl_add_u64 v[82:83], v[122:123], 0, v[82:83]
	v_ashrrev_i32_e32 v85, 31, v84
	v_lshlrev_b64 v[84:85], 13, v[84:85]
	global_store_dwordx4 v[82:83], v[74:77], off
	v_lshl_add_u64 v[84:85], v[146:147], 0, v[84:85]
	s_waitcnt vmcnt(1)
	v_lshlrev_b32_e32 v74, 16, v78
	v_and_b32_e32 v75, 0xffff0000, v78
	v_lshlrev_b32_e32 v76, 16, v79
	v_and_b32_e32 v77, 0xffff0000, v79
	v_lshlrev_b32_e32 v78, 16, v80
	v_and_b32_e32 v79, 0xffff0000, v80
	v_lshlrev_b32_e32 v80, 16, v81
	v_and_b32_e32 v81, 0xffff0000, v81
	v_add_f32_e32 v70, v70, v74
	v_add_f32_e32 v71, v71, v75
	v_add_f32_e32 v72, v72, v76
	v_add_f32_e32 v73, v73, v77
	v_add_f32_e32 v69, v69, v81
	v_add_f32_e32 v74, v66, v78
	v_add_f32_e32 v75, v67, v79
	v_add_f32_e32 v76, v68, v80
	v_cvt_pk_bf16_f32 v66, v70, v71
	v_cvt_pk_bf16_f32 v67, v72, v73
	v_cvt_pk_bf16_f32 v68, v74, v75
	v_cvt_pk_bf16_f32 v69, v76, v69
	global_load_dwordx4 v[70:73], v[84:85], off
	s_nop 0
	global_store_dwordx4 v[82:83], v[66:69], off offset:256
	s_waitcnt vmcnt(1)
	s_nop 0
	v_lshlrev_b32_e32 v66, 16, v70
	v_and_b32_e32 v67, 0xffff0000, v70
	v_lshlrev_b32_e32 v68, 16, v71
	v_and_b32_e32 v69, 0xffff0000, v71
	v_lshlrev_b32_e32 v70, 16, v72
	v_and_b32_e32 v71, 0xffff0000, v72
	v_lshlrev_b32_e32 v72, 16, v73
	v_and_b32_e32 v73, 0xffff0000, v73
	v_add_f32_e32 v62, v62, v66
	v_add_f32_e32 v63, v63, v67
	v_add_f32_e32 v64, v64, v68
	v_add_f32_e32 v65, v65, v69
	v_add_f32_e32 v61, v61, v73
	v_add_f32_e32 v66, v58, v70
	v_add_f32_e32 v67, v59, v71
	v_add_f32_e32 v68, v60, v72
	v_cvt_pk_bf16_f32 v58, v62, v63
	v_cvt_pk_bf16_f32 v59, v64, v65
	v_cvt_pk_bf16_f32 v60, v66, v67
	v_cvt_pk_bf16_f32 v61, v68, v61
	global_load_dwordx4 v[62:65], v[84:85], off offset:256
	v_add_u32_e32 v66, s40, v157
	v_ashrrev_i32_e32 v67, 31, v66
	v_lshlrev_b64 v[66:67], 13, v[66:67]
	v_or_b32_e32 v68, v86, v160
	v_lshl_add_u64 v[66:67], v[122:123], 0, v[66:67]
	v_ashrrev_i32_e32 v69, 31, v68
	v_lshlrev_b64 v[68:69], 13, v[68:69]
	global_store_dwordx4 v[66:67], v[58:61], off
	v_lshl_add_u64 v[68:69], v[146:147], 0, v[68:69]
	s_waitcnt vmcnt(1)
	v_lshlrev_b32_e32 v58, 16, v62
	v_and_b32_e32 v59, 0xffff0000, v62
	v_lshlrev_b32_e32 v60, 16, v63
	v_and_b32_e32 v61, 0xffff0000, v63
	v_lshlrev_b32_e32 v62, 16, v64
	v_and_b32_e32 v63, 0xffff0000, v64
	v_lshlrev_b32_e32 v64, 16, v65
	v_and_b32_e32 v65, 0xffff0000, v65
	v_add_f32_e32 v54, v54, v58
	v_add_f32_e32 v55, v55, v59
	v_add_f32_e32 v56, v56, v60
	v_add_f32_e32 v57, v57, v61
	v_add_f32_e32 v53, v53, v65
	v_add_f32_e32 v58, v50, v62
	v_add_f32_e32 v59, v51, v63
	v_add_f32_e32 v60, v52, v64
	v_cvt_pk_bf16_f32 v50, v54, v55
	v_cvt_pk_bf16_f32 v51, v56, v57
	v_cvt_pk_bf16_f32 v52, v58, v59
	v_cvt_pk_bf16_f32 v53, v60, v53
	global_load_dwordx4 v[54:57], v[68:69], off
	s_nop 0
	global_store_dwordx4 v[66:67], v[50:53], off offset:256
	s_waitcnt vmcnt(1)
; __device__ __forceinline__ float bf_lo(unsigned w) { return __uint_as_float(w << 16); }
; __device__ __forceinline__ float bf_hi(unsigned w) { return __uint_as_float(w & 0xffff0000u); }
; __device__ __forceinline__ v4u pack8(f32x4 a, f32x4 b) { v4u w; w.x = cvt_pk_bf16(a[0], a[1]); w.y = cvt_pk_bf16(a[2], a[3]); w.z = cvt_pk_bf16(b[0], b[1]); w.w = cvt_pk_bf16(b[2], b[3]); return w; }
;     __device__ __forceinline__ void operator()(const f32x4 (&acc)[2][2][4][2], const Unit& u, int wr, int wc, int fr, int fq) const {
;         const bf16* const X1B = (const bf16*)(ws + WS_X1B); bf16* const X2B = (bf16*)(ws + WS_X2B);
;         const int col0 = u.pn * 256 + wc * 32 + 8 * fq;
; #pragma unroll
;         for (int ai = 0; ai < 2; ++ai)
; #pragma unroll
;             for (int m = 0; m < 4; ++m) { const int p = ai * 128 + wr * 64 + m * 16 + fr;
;                 const bf16* sr = X1B + (size_t)(u.pm * 256 + perm_row(p)) * DM + col0; bf16* dr = X2B + (size_t)(u.pm * 256 + p) * DM + col0;
; #pragma unroll
;                 for (int bj = 0; bj < 2; ++bj) { const v4u x = *(const v4u*)(sr + bj * 128); const f32x4 a0 = acc[ai][bj][m][0], a1 = acc[ai][bj][m][1];
;                     const f32x4 v0 = {bf_lo(x.x) + a0[0], bf_hi(x.x) + a0[1], bf_lo(x.y) + a0[2], bf_hi(x.y) + a0[3]};
;                     const f32x4 v1 = {bf_lo(x.z) + a1[0], bf_hi(x.z) + a1[1], bf_lo(x.w) + a1[2], bf_hi(x.w) + a1[3]};
;                     *(v4u*)(dr + bj * 128) = pack8(v0, v1); } }
;     }
	s_nop 0
	v_lshlrev_b32_e32 v50, 16, v54
	v_and_b32_e32 v51, 0xffff0000, v54
	v_lshlrev_b32_e32 v52, 16, v55
	v_and_b32_e32 v53, 0xffff0000, v55
	v_lshlrev_b32_e32 v54, 16, v56
	v_and_b32_e32 v55, 0xffff0000, v56
	v_lshlrev_b32_e32 v56, 16, v57
	v_and_b32_e32 v57, 0xffff0000, v57
	v_add_f32_e32 v46, v46, v50
	v_add_f32_e32 v47, v47, v51
	v_add_f32_e32 v48, v48, v52
	v_add_f32_e32 v49, v49, v53
	v_add_f32_e32 v45, v45, v57
	v_add_f32_e32 v50, v42, v54
	v_add_f32_e32 v51, v43, v55
	v_add_f32_e32 v52, v44, v56
	v_cvt_pk_bf16_f32 v42, v46, v47
	v_cvt_pk_bf16_f32 v43, v48, v49
	v_cvt_pk_bf16_f32 v44, v50, v51
	v_cvt_pk_bf16_f32 v45, v52, v45
	global_load_dwordx4 v[46:49], v[68:69], off offset:256
	v_add_u32_e32 v50, s40, v159
	v_ashrrev_i32_e32 v51, 31, v50
	v_lshlrev_b64 v[50:51], 13, v[50:51]
	v_or_b32_e32 v52, v86, v162
	v_lshl_add_u64 v[50:51], v[122:123], 0, v[50:51]
	v_ashrrev_i32_e32 v53, 31, v52
	v_lshlrev_b64 v[52:53], 13, v[52:53]
	global_store_dwordx4 v[50:51], v[42:45], off
	v_lshl_add_u64 v[52:53], v[146:147], 0, v[52:53]
	s_waitcnt vmcnt(1)
	v_lshlrev_b32_e32 v42, 16, v46
	v_and_b32_e32 v43, 0xffff0000, v46
	v_lshlrev_b32_e32 v44, 16, v47
	v_and_b32_e32 v45, 0xffff0000, v47
	v_lshlrev_b32_e32 v46, 16, v48
	v_and_b32_e32 v47, 0xffff0000, v48
	v_lshlrev_b32_e32 v48, 16, v49
	v_and_b32_e32 v49, 0xffff0000, v49
	v_add_f32_e32 v38, v38, v42
	v_add_f32_e32 v39, v39, v43
	v_add_f32_e32 v40, v40, v44
	v_add_f32_e32 v41, v41, v45
	v_add_f32_e32 v37, v37, v49
	v_add_f32_e32 v42, v34, v46
	v_add_f32_e32 v43, v35, v47
	v_add_f32_e32 v44, v36, v48
	v_cvt_pk_bf16_f32 v34, v38, v39
	v_cvt_pk_bf16_f32 v35, v40, v41
	v_cvt_pk_bf16_f32 v36, v42, v43
	v_cvt_pk_bf16_f32 v37, v44, v37
	global_load_dwordx4 v[38:41], v[52:53], off
	s_nop 0
	global_store_dwordx4 v[50:51], v[34:37], off offset:256
	s_waitcnt vmcnt(1)
	s_nop 0
	v_lshlrev_b32_e32 v34, 16, v38
	v_and_b32_e32 v35, 0xffff0000, v38
	v_lshlrev_b32_e32 v36, 16, v39
	v_and_b32_e32 v37, 0xffff0000, v39
	v_lshlrev_b32_e32 v38, 16, v40
	v_and_b32_e32 v39, 0xffff0000, v40
	v_lshlrev_b32_e32 v40, 16, v41
	v_and_b32_e32 v41, 0xffff0000, v41
	v_add_f32_e32 v30, v30, v34
	v_add_f32_e32 v31, v31, v35
	v_add_f32_e32 v32, v32, v36
	v_add_f32_e32 v33, v33, v37
	v_add_f32_e32 v29, v29, v41
	v_add_f32_e32 v34, v26, v38
	v_add_f32_e32 v35, v27, v39
	v_add_f32_e32 v36, v28, v40
	v_cvt_pk_bf16_f32 v26, v30, v31
	v_cvt_pk_bf16_f32 v27, v32, v33
	v_cvt_pk_bf16_f32 v28, v34, v35
	v_cvt_pk_bf16_f32 v29, v36, v29
	global_load_dwordx4 v[30:33], v[52:53], off offset:256
	v_add_u32_e32 v34, s40, v161
	v_ashrrev_i32_e32 v35, 31, v34
	v_lshlrev_b64 v[34:35], 13, v[34:35]
	v_or_b32_e32 v36, v86, v164
	v_lshl_add_u64 v[34:35], v[122:123], 0, v[34:35]
	v_ashrrev_i32_e32 v37, 31, v36
	v_lshlrev_b64 v[36:37], 13, v[36:37]
	global_store_dwordx4 v[34:35], v[26:29], off
	v_lshl_add_u64 v[36:37], v[146:147], 0, v[36:37]
	s_waitcnt vmcnt(1)
	v_lshlrev_b32_e32 v26, 16, v30
	v_and_b32_e32 v27, 0xffff0000, v30
	v_lshlrev_b32_e32 v28, 16, v31
	v_and_b32_e32 v29, 0xffff0000, v31
	v_lshlrev_b32_e32 v30, 16, v32
	v_and_b32_e32 v31, 0xffff0000, v32
	v_lshlrev_b32_e32 v32, 16, v33
	v_and_b32_e32 v33, 0xffff0000, v33
	v_add_f32_e32 v22, v22, v26
	v_add_f32_e32 v23, v23, v27
	v_add_f32_e32 v24, v24, v28
	v_add_f32_e32 v25, v25, v29
	v_add_f32_e32 v21, v21, v33
	v_add_f32_e32 v26, v18, v30
	v_add_f32_e32 v27, v19, v31
	v_add_f32_e32 v28, v20, v32
	v_cvt_pk_bf16_f32 v18, v22, v23
	v_cvt_pk_bf16_f32 v19, v24, v25
	v_cvt_pk_bf16_f32 v20, v26, v27
	v_cvt_pk_bf16_f32 v21, v28, v21
	global_load_dwordx4 v[22:25], v[36:37], off
	s_nop 0
	global_store_dwordx4 v[34:35], v[18:21], off offset:256
	s_waitcnt vmcnt(1)
	s_nop 0
	v_lshlrev_b32_e32 v18, 16, v22
	v_and_b32_e32 v19, 0xffff0000, v22
	v_lshlrev_b32_e32 v20, 16, v23
	v_and_b32_e32 v21, 0xffff0000, v23
	v_lshlrev_b32_e32 v22, 16, v24
	v_and_b32_e32 v23, 0xffff0000, v24
	v_lshlrev_b32_e32 v24, 16, v25
	v_and_b32_e32 v25, 0xffff0000, v25
	v_add_f32_e32 v14, v14, v18
	v_add_f32_e32 v15, v15, v19
	v_add_f32_e32 v16, v16, v20
	v_add_f32_e32 v17, v17, v21
	v_add_f32_e32 v13, v13, v25
	v_add_f32_e32 v18, v10, v22
	v_add_f32_e32 v19, v11, v23
	v_add_f32_e32 v20, v12, v24
	v_cvt_pk_bf16_f32 v10, v14, v15
	v_cvt_pk_bf16_f32 v11, v16, v17
	v_cvt_pk_bf16_f32 v12, v18, v19
	v_cvt_pk_bf16_f32 v13, v20, v13
	global_load_dwordx4 v[14:17], v[36:37], off offset:256
	v_add_u32_e32 v18, s40, v163
	v_ashrrev_i32_e32 v19, 31, v18
	v_lshlrev_b64 v[18:19], 13, v[18:19]
	v_lshl_add_u64 v[18:19], v[122:123], 0, v[18:19]
	global_store_dwordx4 v[18:19], v[10:13], off
	s_waitcnt vmcnt(1)
	s_nop 0
	v_lshlrev_b32_e32 v10, 16, v14
	v_and_b32_e32 v11, 0xffff0000, v14
	v_lshlrev_b32_e32 v12, 16, v15
	v_and_b32_e32 v13, 0xffff0000, v15
	v_lshlrev_b32_e32 v14, 16, v16
	v_and_b32_e32 v15, 0xffff0000, v16
	v_lshlrev_b32_e32 v16, 16, v17
	v_and_b32_e32 v17, 0xffff0000, v17
	v_add_f32_e32 v5, v5, v17
	v_add_f32_e32 v6, v6, v10
	v_add_f32_e32 v7, v7, v11
	v_add_f32_e32 v8, v8, v12
	v_add_f32_e32 v9, v9, v13
	v_add_f32_e32 v10, v2, v14
	v_add_f32_e32 v11, v3, v15
	v_add_f32_e32 v12, v4, v16
	v_cvt_pk_bf16_f32 v2, v6, v7
	v_cvt_pk_bf16_f32 v3, v8, v9
	v_cvt_pk_bf16_f32 v4, v10, v11
	v_cvt_pk_bf16_f32 v5, v12, v5
	global_store_dwordx4 v[18:19], v[2:5], off offset:256
	s_cbranch_vccnz .LBB0_1719
	s_andn2_b64 vcc, exec, s[8:9]
	s_cbranch_vccnz .LBB0_1718
	s_barrier
	s_branch .LBB0_1718

; #define GAS __attribute__((address_space(1)))
; #define INP(i) in_ptr(F.ka, (i))
; __device__ __forceinline__ void p10_final(Frame& F) {
;     const int gw = F.vcu * NWAVES + F.wave, NGW = F.G * NWAVES;
;     const GAS f32x4* gr = (const GAS f32x4*)INP(19) + F.lane;
;     constexpr size_t PL = (size_t)MS * DM / 4;
.LBB0_1802:
	s_or_b64 exec, exec, s[2:3]
	v_readlane_b32 s2, v255, 7
	v_readlane_b32 s3, v255, 8
	s_andn2_b64 vcc, exec, s[2:3]
	s_waitcnt lgkmcnt(0)
	s_barrier
	s_cbranch_vccnz .LBB0_1809
	s_load_dwordx2 s[0:1], s[0:1], 0x98
	v_mbcnt_hi_u32_b32 v0, -1, v254
	v_and_b32_e32 v1, 64, v0
	v_add_u32_e32 v1, 64, v1
	v_xor_b32_e32 v2, 1, v0
	v_mov_b32_e32 v201, 0
	v_cmp_lt_i32_e32 vcc, v2, v1
	s_waitcnt lgkmcnt(0)
	v_lshl_add_u64 v[84:85], s[0:1], 0, v[200:201]
	s_and_b32 s98, s24, 7
	s_lshl_b32 s98, s98, 14
	v_lshl_add_u32 v230, v0, 4, s98
	v_lshlrev_b32_e32 v231, 4, v0
	global_load_dwordx4 v[232:235], v231, s[0:1]
	global_load_dwordx4 v[236:239], v231, s[0:1] offset:1024
	global_load_dwordx4 v[240:243], v231, s[0:1] offset:2048
	global_load_dwordx4 v[244:247], v231, s[0:1] offset:3072
	s_waitcnt vmcnt(0)
	ds_write_b128 v230, v[232:235]
	ds_write_b128 v230, v[236:239] offset:1024
	ds_write_b128 v230, v[240:243] offset:2048
	ds_write_b128 v230, v[244:247] offset:3072
	s_waitcnt lgkmcnt(0)
	v_add_u32_e32 v231, 0x1000, v231
	global_load_dwordx4 v[232:235], v231, s[0:1]
	global_load_dwordx4 v[236:239], v231, s[0:1] offset:1024
	global_load_dwordx4 v[240:243], v231, s[0:1] offset:2048
	global_load_dwordx4 v[244:247], v231, s[0:1] offset:3072
	s_waitcnt vmcnt(0)
	ds_write_b128 v230, v[232:235] offset:4096
	ds_write_b128 v230, v[236:239] offset:5120
	ds_write_b128 v230, v[240:243] offset:6144
	ds_write_b128 v230, v[244:247] offset:7168
	s_waitcnt lgkmcnt(0)
	v_add_u32_e32 v231, 0x1000, v231
	global_load_dwordx4 v[232:235], v231, s[0:1]
	global_load_dwordx4 v[236:239], v231, s[0:1] offset:1024
	global_load_dwordx4 v[240:243], v231, s[0:1] offset:2048
	global_load_dwordx4 v[244:247], v231, s[0:1] offset:3072
	s_waitcnt vmcnt(0)
	ds_write_b128 v230, v[232:235] offset:8192
	ds_write_b128 v230, v[236:239] offset:9216
	ds_write_b128 v230, v[240:243] offset:10240
	ds_write_b128 v230, v[244:247] offset:11264
	s_waitcnt lgkmcnt(0)
	v_add_u32_e32 v231, 0x1000, v231
	global_load_dwordx4 v[232:235], v231, s[0:1]
	global_load_dwordx4 v[236:239], v231, s[0:1] offset:1024
	global_load_dwordx4 v[240:243], v231, s[0:1] offset:2048
	global_load_dwordx4 v[244:247], v231, s[0:1] offset:3072
	s_waitcnt vmcnt(0)
	ds_write_b128 v230, v[232:235] offset:12288
	ds_write_b128 v230, v[236:239] offset:13312
	ds_write_b128 v230, v[240:243] offset:14336
	ds_write_b128 v230, v[244:247] offset:15360
	s_waitcnt lgkmcnt(0)
	s_mov_b64 s[0:1], 0x1000
	v_cndmask_b32_e32 v2, v0, v2, vcc
	v_lshlrev_b32_e32 v144, 2, v2
	v_xor_b32_e32 v2, 2, v0
	v_lshl_add_u64 v[86:87], v[84:85], 0, s[0:1]
	s_mov_b64 s[0:1], 0x1400
	v_cmp_lt_i32_e32 vcc, v2, v1
	v_lshl_add_u64 v[88:89], v[84:85], 0, s[0:1]
	s_mov_b64 s[0:1], 0x1800
	v_cndmask_b32_e32 v2, v0, v2, vcc
	v_lshl_add_u64 v[90:91], v[84:85], 0, s[0:1]
	s_mov_b64 s[0:1], 0x1c00
	v_lshlrev_b32_e32 v145, 2, v2
	v_xor_b32_e32 v2, 4, v0
	v_lshl_add_u64 v[92:93], v[84:85], 0, s[0:1]
	s_mov_b64 s[0:1], 0x2000
	v_cmp_lt_i32_e32 vcc, v2, v1
	v_lshl_add_u64 v[94:95], v[84:85], 0, s[0:1]
	s_mov_b64 s[0:1], 0x2400
	v_cndmask_b32_e32 v2, v0, v2, vcc
	v_lshl_add_u64 v[96:97], v[84:85], 0, s[0:1]
	s_mov_b64 s[0:1], 0x2800
	v_lshlrev_b32_e32 v146, 2, v2
	v_xor_b32_e32 v2, 8, v0
	v_lshl_add_u64 v[98:99], v[84:85], 0, s[0:1]
	s_mov_b64 s[0:1], 0x2c00
	v_cmp_lt_i32_e32 vcc, v2, v1
	v_lshl_add_u64 v[100:101], v[84:85], 0, s[0:1]
	s_mov_b64 s[0:1], 0x3000
	v_cndmask_b32_e32 v2, v0, v2, vcc
	v_lshl_add_u64 v[102:103], v[84:85], 0, s[0:1]
	s_mov_b64 s[0:1], 0x3400
	v_lshlrev_b32_e32 v147, 2, v2
	v_xor_b32_e32 v2, 16, v0
	v_lshl_add_u64 v[104:105], v[84:85], 0, s[0:1]
	s_mov_b64 s[0:1], 0x3800
	v_cmp_lt_i32_e32 vcc, v2, v1
	v_lshl_add_u64 v[106:107], v[84:85], 0, s[0:1]
	s_mov_b64 s[0:1], 0x3c00
	v_cndmask_b32_e32 v2, v0, v2, vcc
	v_lshl_add_u64 v[108:109], v[84:85], 0, s[0:1]
	v_readlane_b32 s0, v255, 14
	v_lshlrev_b32_e32 v148, 2, v2
	v_xor_b32_e32 v2, 32, v0
	v_readlane_b32 s1, v255, 15
	s_ashr_i32 s25, s24, 31
	v_cmp_lt_i32_e32 vcc, v2, v1
	v_lshl_add_u64 v[112:113], s[0:1], 0, v[200:201]
	s_ashr_i32 s95, s94, 31
	s_lshl_b64 s[0:1], s[24:25], 13
	v_cndmask_b32_e32 v0, v0, v2, vcc
	s_add_u32 s0, s22, s0
	v_lshlrev_b32_e32 v149, 2, v0
	v_lshlrev_b32_e32 v0, 3, v248
	v_mov_b32_e32 v1, v201
	s_addc_u32 s1, s23, s1
	v_lshl_add_u64 v[110:111], s[14:15], 0, v[0:1]
	v_lshl_add_u64 v[0:1], s[0:1], 0, v[0:1]
	s_mov_b64 s[0:1], 0x1cc00000
	s_mov_b32 s3, 0
	v_lshl_add_u64 v[114:115], s[20:21], 0, v[200:201]
	v_lshl_add_u64 v[116:117], v[0:1], 0, s[0:1]
	s_lshl_b64 s[4:5], s[94:95], 13
	s_mov_b32 s8, 0x1000000
	s_brev_b32 s9, 64
	s_mov_b32 s10, 0x3000000
	s_movk_i32 s11, 0x1000
	s_mov_b32 s12, 0x1001000
	s_mov_b32 s13, 0x2001000
	s_mov_b32 s14, 0x3001000
	s_movk_i32 s15, 0x2000
	s_mov_b32 s16, 0x1002000
	s_mov_b32 s17, 0x2002000
	s_mov_b32 s18, 0x3002000
	s_movk_i32 s19, 0x3000
	s_mov_b32 s20, 0x1003000
	s_mov_b32 s21, 0x2003000
	s_mov_b32 s22, 0x3003000
	v_mov_b32_e32 v150, 0x358637bd
	s_mov_b32 s23, 0xf800000
	v_mov_b32_e32 v151, 0x260
	s_branch .LBB0_1805
; #define GAS __attribute__((address_space(1)))
; __device__ __forceinline__ void p10_final(Frame& F) {
;     ...
;         float s = 0.f;
; #pragma unroll
;         for (int j = 0; j < 16; ++j) s += (v[j].x * v[j].x + v[j].y * v[j].y) + (v[j].z * v[j].z + v[j].w * v[j].w);
;         const float r = 1.f / sqrtf(wave_sum(s) * (1.f / DM) + EPS);
;         GAS f32x4* orow = (GAS f32x4*)(F.out + (size_t)m * DM) + F.lane;
; #pragma unroll
;         for (int j = 0; j < 16; ++j) orow[64 * j] = v[j] * r * gr[64 * j];
.LBB0_1804:
	v_pk_mul_f32 v[64:65], v[6:7], v[6:7]
	v_pk_mul_f32 v[66:67], v[4:5], v[4:5]
	v_lshl_add_u64 v[116:117], v[116:117], 0, s[4:5]
	v_pk_mov_b32 v[68:69], v[66:67], v[64:65] op_sel:[1,0]
	v_mov_b32_e32 v67, v65
	v_pk_add_f32 v[64:65], v[68:69], v[66:67]
	v_pk_mul_f32 v[66:67], v[2:3], v[2:3]
	v_pk_add_f32 v[64:65], v[64:65], v[64:65] op_sel_hi:[0,1]
	v_pk_mul_f32 v[68:69], v[0:1], v[0:1]
	v_mul_f32_e32 v64, v12, v12
	v_pk_mov_b32 v[70:71], v[68:69], v[66:67] op_sel:[1,0]
	v_mov_b32_e32 v69, v67
	v_pk_add_f32 v[66:67], v[70:71], v[68:69]
	v_pk_fma_f32 v[68:69], v[12:13], v[12:13], v[64:65] op_sel_hi:[1,1,0]
	v_mul_f32_e32 v64, v14, v14
	v_pk_add_f32 v[66:67], v[66:67], v[66:67] op_sel_hi:[0,1]
	v_pk_fma_f32 v[70:71], v[14:15], v[14:15], v[64:65] op_sel_hi:[1,1,0]
	v_mul_f32_e32 v68, v16, v16
	v_mul_f32_e32 v70, v17, v17
	v_mul_f32_e32 v66, v18, v18
	v_mul_f32_e32 v64, v19, v19
	v_pk_add_f32 v[68:69], v[68:69], v[70:71]
	v_pk_add_f32 v[64:65], v[66:67], v[64:65]
	v_pk_mul_f32 v[66:67], v[10:11], v[10:11]
	v_pk_add_f32 v[64:65], v[68:69], v[64:65]
	v_pk_mul_f32 v[68:69], v[8:9], v[8:9]
	v_pk_add_f32 v[64:65], v[64:65], v[64:65] op_sel_hi:[0,1]
	v_pk_mov_b32 v[70:71], v[68:69], v[66:67] op_sel:[1,0]
	v_mov_b32_e32 v69, v67
	v_mul_f32_e32 v64, v20, v20
	v_pk_add_f32 v[66:67], v[70:71], v[68:69]
	v_pk_fma_f32 v[68:69], v[20:21], v[20:21], v[64:65] op_sel_hi:[1,1,0]
	v_mul_f32_e32 v64, v22, v22
	v_pk_add_f32 v[66:67], v[66:67], v[66:67] op_sel_hi:[0,1]
	v_pk_fma_f32 v[70:71], v[22:23], v[22:23], v[64:65] op_sel_hi:[1,1,0]
	v_mul_f32_e32 v68, v24, v24
	v_mul_f32_e32 v70, v25, v25
	v_mul_f32_e32 v66, v26, v26
	v_mul_f32_e32 v64, v27, v27
	v_pk_add_f32 v[68:69], v[68:69], v[70:71]
	v_pk_add_f32 v[64:65], v[66:67], v[64:65]
	v_pk_mul_f32 v[66:67], v[30:31], v[30:31]
	v_pk_add_f32 v[64:65], v[68:69], v[64:65]
	v_pk_mul_f32 v[68:69], v[28:29], v[28:29]
	v_pk_add_f32 v[64:65], v[64:65], v[64:65] op_sel_hi:[0,1]
	v_pk_mov_b32 v[70:71], v[68:69], v[66:67] op_sel:[1,0]
	v_mov_b32_e32 v69, v67
	v_mul_f32_e32 v64, v36, v36
	v_pk_add_f32 v[66:67], v[70:71], v[68:69]
	v_pk_fma_f32 v[68:69], v[36:37], v[36:37], v[64:65] op_sel_hi:[1,1,0]
	v_mul_f32_e32 v64, v38, v38
	v_pk_add_f32 v[66:67], v[66:67], v[66:67] op_sel_hi:[0,1]
	v_pk_fma_f32 v[70:71], v[38:39], v[38:39], v[64:65] op_sel_hi:[1,1,0]
	v_mul_f32_e32 v68, v44, v44
	v_mul_f32_e32 v70, v45, v45
	v_mul_f32_e32 v66, v46, v46
	v_mul_f32_e32 v64, v47, v47
	v_pk_add_f32 v[68:69], v[68:69], v[70:71]
	v_pk_add_f32 v[64:65], v[66:67], v[64:65]
	v_pk_mul_f32 v[66:67], v[50:51], v[50:51]
	v_pk_add_f32 v[64:65], v[68:69], v[64:65]
	v_pk_mul_f32 v[68:69], v[48:49], v[48:49]
	v_pk_add_f32 v[64:65], v[64:65], v[64:65] op_sel_hi:[0,1]
	v_pk_mov_b32 v[70:71], v[68:69], v[66:67] op_sel:[1,0]
	v_mov_b32_e32 v69, v67
	v_mul_f32_e32 v64, v56, v56
	v_pk_add_f32 v[66:67], v[70:71], v[68:69]
	v_pk_fma_f32 v[68:69], v[56:57], v[56:57], v[64:65] op_sel_hi:[1,1,0]
	v_mul_f32_e32 v64, v58, v58
	v_pk_add_f32 v[66:67], v[66:67], v[66:67] op_sel_hi:[0,1]
	v_pk_fma_f32 v[70:71], v[58:59], v[58:59], v[64:65] op_sel_hi:[1,1,0]
	v_mul_f32_e32 v68, v32, v32
	v_mul_f32_e32 v70, v33, v33
	v_mul_f32_e32 v66, v34, v34
	v_mul_f32_e32 v64, v35, v35
	v_pk_add_f32 v[68:69], v[68:69], v[70:71]
	v_pk_add_f32 v[64:65], v[66:67], v[64:65]
	v_pk_mul_f32 v[66:67], v[54:55], v[54:55]
	v_pk_add_f32 v[64:65], v[68:69], v[64:65]
	v_pk_mul_f32 v[68:69], v[52:53], v[52:53]
	v_pk_add_f32 v[64:65], v[64:65], v[64:65] op_sel_hi:[0,1]
	v_pk_mov_b32 v[70:71], v[68:69], v[66:67] op_sel:[1,0]
	v_mov_b32_e32 v69, v67
	v_mul_f32_e32 v64, v60, v60
	v_pk_add_f32 v[66:67], v[70:71], v[68:69]
	v_pk_fma_f32 v[68:69], v[60:61], v[60:61], v[64:65] op_sel_hi:[1,1,0]
	v_mul_f32_e32 v64, v62, v62
	v_pk_add_f32 v[66:67], v[66:67], v[66:67] op_sel_hi:[0,1]
	v_pk_fma_f32 v[70:71], v[62:63], v[62:63], v[64:65] op_sel_hi:[1,1,0]
	v_mul_f32_e32 v68, v40, v40
	v_mul_f32_e32 v70, v41, v41
	v_mul_f32_e32 v66, v42, v42
	v_mul_f32_e32 v64, v43, v43
	v_pk_add_f32 v[70:71], v[68:69], v[70:71]
	v_pk_add_f32 v[64:65], v[66:67], v[64:65]
	ds_read_b128 v[66:69], v230
	v_pk_add_f32 v[64:65], v[70:71], v[64:65]
	s_nop 0
	v_add_f32_e32 v64, v64, v65
	ds_bpermute_b32 v65, v144, v64
	s_waitcnt lgkmcnt(0)
	v_add_f32_e32 v64, v64, v65
	ds_bpermute_b32 v65, v145, v64
	s_waitcnt lgkmcnt(0)
	v_add_f32_e32 v64, v64, v65
	ds_bpermute_b32 v65, v146, v64
	s_waitcnt lgkmcnt(0)
	v_add_f32_e32 v64, v64, v65
	ds_bpermute_b32 v65, v147, v64
	s_waitcnt lgkmcnt(0)
	v_add_f32_e32 v64, v64, v65
	ds_bpermute_b32 v65, v148, v64
	s_waitcnt lgkmcnt(0)
	v_add_f32_e32 v64, v64, v65
	ds_bpermute_b32 v65, v149, v64
	s_waitcnt lgkmcnt(0)
	v_add_f32_e32 v64, v64, v65
	v_fmamk_f32 v64, v64, 0x39800000, v150
	v_mul_f32_e32 v65, 0x4f800000, v64
	v_cmp_gt_f32_e32 vcc, s23, v64
	s_nop 1
	v_cndmask_b32_e32 v64, v64, v65, vcc
	v_sqrt_f32_e32 v65, v64
	s_nop 0
	v_add_u32_e32 v70, -1, v65
	v_fma_f32 v71, -v70, v65, v64
	v_cmp_ge_f32_e64 s[0:1], 0, v71
	v_add_u32_e32 v71, 1, v65
	s_nop 0
	v_cndmask_b32_e64 v70, v65, v70, s[0:1]
	v_fma_f32 v65, -v71, v65, v64
	v_cmp_lt_f32_e64 s[0:1], 0, v65
	s_nop 1
	v_cndmask_b32_e64 v65, v70, v71, s[0:1]
	v_mul_f32_e32 v70, 0x37800000, v65
	v_cndmask_b32_e32 v65, v65, v70, vcc
	v_cmp_class_f32_e32 vcc, v64, v151
	s_nop 1
	v_cndmask_b32_e32 v64, v65, v64, vcc
	v_div_scale_f32 v65, s[0:1], v64, v64, 1.0
	v_rcp_f32_e32 v70, v65
	s_lshl_b64 s[0:1], s[6:7], 14
	s_add_u32 s24, s24, s94
	s_addc_u32 s25, s25, s95
	v_fma_f32 v71, -v65, v70, 1.0
	v_fmac_f32_e32 v70, v71, v70
	v_div_scale_f32 v71, vcc, 1.0, v64, 1.0
	v_mul_f32_e32 v72, v71, v70
	v_fma_f32 v73, -v65, v72, v71
	v_fmac_f32_e32 v72, v73, v70
	v_fma_f32 v65, -v65, v72, v71
	v_div_fmas_f32 v65, v65, v70, v72
	v_div_fixup_f32 v64, v65, v64, 1.0
	v_pk_mul_f32 v[4:5], v[4:5], v[64:65] op_sel_hi:[1,0]
	v_pk_mul_f32 v[6:7], v[6:7], v[64:65] op_sel_hi:[1,0]
	v_lshl_add_u64 v[70:71], v[114:115], 0, s[0:1]
	s_waitcnt lgkmcnt(0)
; __device__ __forceinline__ void p10_final(Frame& F) {
;     ...
; #pragma unroll
;         for (int j = 0; j < 16; ++j) orow[64 * j] = v[j] * r * gr[64 * j];
	v_pk_mul_f32 v[6:7], v[68:69], v[6:7]
	v_pk_mul_f32 v[4:5], v[66:67], v[4:5]
	global_store_dwordx4 v[70:71], v[4:7], off
	s_nop 0
	ds_read_b128 v[4:7], v230 offset:1024
	v_pk_mul_f32 v[2:3], v[2:3], v[64:65] op_sel_hi:[1,0]
	v_pk_mul_f32 v[0:1], v[0:1], v[64:65] op_sel_hi:[1,0]
	v_pk_mul_f32 v[8:9], v[8:9], v[64:65] op_sel_hi:[1,0]
	s_cmpk_lt_i32 s24, 0x4400
	s_waitcnt lgkmcnt(0)
	v_pk_mul_f32 v[0:1], v[4:5], v[0:1]
	v_pk_mul_f32 v[2:3], v[6:7], v[2:3]
	global_store_dwordx4 v[70:71], v[0:3], off offset:1024
	s_nop 0
	ds_read_b128 v[0:3], v230 offset:2048
	v_pk_mul_f32 v[4:5], v[14:15], v[64:65] op_sel_hi:[1,0]
	v_pk_mul_f32 v[6:7], v[12:13], v[64:65] op_sel_hi:[1,0]
	s_waitcnt lgkmcnt(0)
	v_pk_mul_f32 v[2:3], v[2:3], v[4:5]
	v_pk_mul_f32 v[0:1], v[0:1], v[6:7]
	global_store_dwordx4 v[70:71], v[0:3], off offset:2048
	s_nop 0
	ds_read_b128 v[0:3], v230 offset:3072
	v_pk_mul_f32 v[4:5], v[18:19], v[64:65] op_sel_hi:[1,0]
	v_pk_mul_f32 v[6:7], v[16:17], v[64:65] op_sel_hi:[1,0]
	s_waitcnt lgkmcnt(0)
	v_pk_mul_f32 v[2:3], v[2:3], v[4:5]
	v_pk_mul_f32 v[0:1], v[0:1], v[6:7]
	global_store_dwordx4 v[70:71], v[0:3], off offset:3072
	s_nop 0
	ds_read_b128 v[0:3], v230 offset:4096
	v_add_co_u32_e32 v4, vcc, s15, v70
	v_pk_mul_f32 v[6:7], v[10:11], v[64:65] op_sel_hi:[1,0]
	s_nop 0
	v_addc_co_u32_e32 v5, vcc, 0, v71, vcc
	v_pk_mul_f32 v[10:11], v[20:21], v[64:65] op_sel_hi:[1,0]
	s_waitcnt lgkmcnt(0)
	v_pk_mul_f32 v[0:1], v[0:1], v[8:9]
	v_pk_mul_f32 v[2:3], v[2:3], v[6:7]
	global_store_dwordx4 v[4:5], v[0:3], off offset:-4096
	s_nop 0
	ds_read_b128 v[0:3], v230 offset:5120
	v_add_co_u32_e32 v6, vcc, s11, v70
	v_pk_mul_f32 v[8:9], v[22:23], v[64:65] op_sel_hi:[1,0]
	s_nop 0
	v_addc_co_u32_e32 v7, vcc, 0, v71, vcc
	s_waitcnt lgkmcnt(0)
	v_pk_mul_f32 v[0:1], v[0:1], v[10:11]
	v_pk_mul_f32 v[2:3], v[2:3], v[8:9]
	global_store_dwordx4 v[6:7], v[0:3], off offset:1024
	s_nop 0
	ds_read_b128 v[0:3], v230 offset:6144
	v_pk_mul_f32 v[8:9], v[26:27], v[64:65] op_sel_hi:[1,0]
	v_pk_mul_f32 v[10:11], v[24:25], v[64:65] op_sel_hi:[1,0]
	s_waitcnt lgkmcnt(0)
	v_pk_mul_f32 v[2:3], v[2:3], v[8:9]
	v_pk_mul_f32 v[0:1], v[0:1], v[10:11]
	global_store_dwordx4 v[6:7], v[0:3], off offset:2048
	s_nop 0
	ds_read_b128 v[0:3], v230 offset:7168
	v_pk_mul_f32 v[8:9], v[30:31], v[64:65] op_sel_hi:[1,0]
	v_pk_mul_f32 v[10:11], v[28:29], v[64:65] op_sel_hi:[1,0]
	s_waitcnt lgkmcnt(0)
	v_pk_mul_f32 v[2:3], v[2:3], v[8:9]
	v_pk_mul_f32 v[0:1], v[0:1], v[10:11]
	global_store_dwordx4 v[6:7], v[0:3], off offset:3072
	s_nop 0
	ds_read_b128 v[0:3], v230 offset:8192
	v_pk_mul_f32 v[6:7], v[38:39], v[64:65] op_sel_hi:[1,0]
	v_pk_mul_f32 v[8:9], v[36:37], v[64:65] op_sel_hi:[1,0]
	s_waitcnt lgkmcnt(0)
	v_pk_mul_f32 v[2:3], v[2:3], v[6:7]
	v_pk_mul_f32 v[0:1], v[0:1], v[8:9]
	global_store_dwordx4 v[4:5], v[0:3], off
	s_nop 0
	ds_read_b128 v[0:3], v230 offset:9216
	v_pk_mul_f32 v[6:7], v[46:47], v[64:65] op_sel_hi:[1,0]
	v_pk_mul_f32 v[8:9], v[44:45], v[64:65] op_sel_hi:[1,0]
	s_waitcnt lgkmcnt(0)
	v_pk_mul_f32 v[2:3], v[2:3], v[6:7]
	v_pk_mul_f32 v[0:1], v[0:1], v[8:9]
	global_store_dwordx4 v[4:5], v[0:3], off offset:1024
	s_nop 0
	ds_read_b128 v[0:3], v230 offset:10240
	v_pk_mul_f32 v[6:7], v[50:51], v[64:65] op_sel_hi:[1,0]
	v_pk_mul_f32 v[8:9], v[48:49], v[64:65] op_sel_hi:[1,0]
	s_waitcnt lgkmcnt(0)
	v_pk_mul_f32 v[2:3], v[2:3], v[6:7]
	v_pk_mul_f32 v[0:1], v[0:1], v[8:9]
	global_store_dwordx4 v[4:5], v[0:3], off offset:2048
	s_nop 0
	ds_read_b128 v[0:3], v230 offset:11264
	v_pk_mul_f32 v[6:7], v[58:59], v[64:65] op_sel_hi:[1,0]
	v_pk_mul_f32 v[8:9], v[56:57], v[64:65] op_sel_hi:[1,0]
	s_waitcnt lgkmcnt(0)
	v_pk_mul_f32 v[2:3], v[2:3], v[6:7]
	v_pk_mul_f32 v[0:1], v[0:1], v[8:9]
	global_store_dwordx4 v[4:5], v[0:3], off offset:3072
	s_nop 0
	ds_read_b128 v[0:3], v230 offset:12288
	v_add_co_u32_e32 v4, vcc, s19, v70
	v_pk_mul_f32 v[6:7], v[34:35], v[64:65] op_sel_hi:[1,0]
	v_pk_mul_f32 v[8:9], v[32:33], v[64:65] op_sel_hi:[1,0]
	v_addc_co_u32_e32 v5, vcc, 0, v71, vcc
	s_waitcnt lgkmcnt(0)
	v_pk_mul_f32 v[0:1], v[0:1], v[8:9]
	v_pk_mul_f32 v[2:3], v[2:3], v[6:7]
	global_store_dwordx4 v[4:5], v[0:3], off
	s_nop 0
	ds_read_b128 v[0:3], v230 offset:13312
	v_pk_mul_f32 v[6:7], v[54:55], v[64:65] op_sel_hi:[1,0]
	v_pk_mul_f32 v[8:9], v[52:53], v[64:65] op_sel_hi:[1,0]
	s_waitcnt lgkmcnt(0)
	v_pk_mul_f32 v[2:3], v[6:7], v[2:3]
	v_pk_mul_f32 v[0:1], v[8:9], v[0:1]
	global_store_dwordx4 v[4:5], v[0:3], off offset:1024
	s_nop 0
	ds_read_b128 v[0:3], v230 offset:14336
	v_pk_mul_f32 v[6:7], v[62:63], v[64:65] op_sel_hi:[1,0]
	v_pk_mul_f32 v[8:9], v[60:61], v[64:65] op_sel_hi:[1,0]
	s_waitcnt lgkmcnt(0)
	v_pk_mul_f32 v[2:3], v[6:7], v[2:3]
	v_pk_mul_f32 v[0:1], v[8:9], v[0:1]
	global_store_dwordx4 v[4:5], v[0:3], off offset:2048
	s_nop 0
	ds_read_b128 v[0:3], v230 offset:15360
	v_pk_mul_f32 v[6:7], v[42:43], v[64:65] op_sel_hi:[1,0]
	v_pk_mul_f32 v[8:9], v[40:41], v[64:65] op_sel_hi:[1,0]
	s_waitcnt lgkmcnt(0)
	v_pk_mul_f32 v[2:3], v[6:7], v[2:3]
	v_pk_mul_f32 v[0:1], v[8:9], v[0:1]
	global_store_dwordx4 v[4:5], v[0:3], off offset:3072
	s_cbranch_scc0 .LBB0_1809

; __global__ void __launch_bounds__(NTHREADS, 2) fwd_kernel(Args args) {
	.amdhsa_kernel _Z10fwd_kernel4Args
		.amdhsa_group_segment_fixed_size 0
		.amdhsa_private_segment_fixed_size 0
		.amdhsa_kernarg_size 432
		.amdhsa_user_sgpr_count 2
		.amdhsa_user_sgpr_dispatch_ptr 0
		.amdhsa_user_sgpr_queue_ptr 0
		.amdhsa_user_sgpr_kernarg_segment_ptr 1
		.amdhsa_user_sgpr_dispatch_id 0
		.amdhsa_user_sgpr_kernarg_preload_length 0
		.amdhsa_user_sgpr_kernarg_preload_offset 0
		.amdhsa_user_sgpr_private_segment_size 0
		.amdhsa_uses_dynamic_stack 0
		.amdhsa_enable_private_segment 0
		.amdhsa_system_sgpr_workgroup_id_x 1
		.amdhsa_system_sgpr_workgroup_id_y 0
		.amdhsa_system_sgpr_workgroup_id_z 0
		.amdhsa_system_sgpr_workgroup_info 0
		.amdhsa_system_vgpr_workitem_id 0
		.amdhsa_next_free_vgpr 256
		.amdhsa_next_free_sgpr 102
		.amdhsa_accum_offset 256
		.amdhsa_reserve_vcc 1
		.amdhsa_float_round_mode_32 0
		.amdhsa_float_round_mode_16_64 0
		.amdhsa_float_denorm_mode_32 3
		.amdhsa_float_denorm_mode_16_64 3
		.amdhsa_dx10_clamp 1
		.amdhsa_ieee_mode 1
		.amdhsa_fp16_overflow 0
		.amdhsa_tg_split 0
		.amdhsa_exception_fp_ieee_invalid_op 0
		.amdhsa_exception_fp_denorm_src 0
		.amdhsa_exception_fp_ieee_div_zero 0
		.amdhsa_exception_fp_ieee_overflow 0
		.amdhsa_exception_fp_ieee_underflow 0
		.amdhsa_exception_fp_ieee_inexact 0
		.amdhsa_exception_int_div_zero 0
	.end_amdhsa_kernel

; __global__ void __launch_bounds__(NTHREADS, 2) fwd_kernel(Args args) {
amdhsa.kernels:
  - .agpr_count:     0
    .args:
      - .offset:         0
        .size:           176
        .value_kind:     by_value
      - .offset:         176
        .size:           4
        .value_kind:     hidden_block_count_x
      - .offset:         180
        .size:           4
        .value_kind:     hidden_block_count_y
      - .offset:         184
        .size:           4
        .value_kind:     hidden_block_count_z
      - .offset:         188
        .size:           2
        .value_kind:     hidden_group_size_x
      - .offset:         190
        .size:           2
        .value_kind:     hidden_group_size_y
      - .offset:         192
        .size:           2
        .value_kind:     hidden_group_size_z
      - .offset:         194
        .size:           2
        .value_kind:     hidden_remainder_x
      - .offset:         196
        .size:           2
        .value_kind:     hidden_remainder_y
      - .offset:         198
        .size:           2
        .value_kind:     hidden_remainder_z
      - .offset:         216
        .size:           8
        .value_kind:     hidden_global_offset_x
      - .offset:         224
        .size:           8
        .value_kind:     hidden_global_offset_y
      - .offset:         232
        .size:           8
        .value_kind:     hidden_global_offset_z
      - .offset:         240
        .size:           2
        .value_kind:     hidden_grid_dims
      - .offset:         296
        .size:           4
        .value_kind:     hidden_dynamic_lds_size
    .group_segment_fixed_size: 0
    .kernarg_segment_align: 8
    .kernarg_segment_size: 432
    .language:       OpenCL C
    .language_version:
      - 2
      - 0
    .max_flat_workgroup_size: 512
    .name:           _Z10fwd_kernel4Args
    .private_segment_fixed_size: 0
    .sgpr_count:     108
    .sgpr_spill_count: 42
    .symbol:         _Z10fwd_kernel4Args.kd
    .uniform_work_group_size: 1
    .uses_dynamic_stack: false
    .vgpr_count:     256
    .vgpr_spill_count: 0
    .wavefront_size: 64
